# T1: attention staging tail (vmcnt, 4 ds_write, address SALU, 4 global loads) interleaved into the gaps between PV MFMAs; tile loads unconditional; on top of R1+C1+AT1
# speedup vs baseline: 1.0129x; 1.0007x over previous
.LBB0_633:
	s_waitcnt lgkmcnt(0)
	s_barrier
	v_lshl_add_u32 v187, s53, 14, v173
	ds_read_b64_tr_b16 v[188:189], v187 offset:0
	ds_read_b64_tr_b16 v[190:191], v187 offset:0x800
	ds_read_b64_tr_b16 v[192:193], v187 offset:0x1000
	ds_read_b64_tr_b16 v[194:195], v187 offset:0x1800
	ds_read_b64_tr_b16 v[196:197], v187 offset:0x2000
	ds_read_b64_tr_b16 v[198:199], v187 offset:0x2800
	ds_read_b64_tr_b16 v[200:201], v187 offset:0x3000
	ds_read_b64_tr_b16 v[202:203], v187 offset:0x3800
	s_lshl_b32 s52, s49, 14
	v_add_u32_e32 v208, s52, v174
	ds_read_b128 v[68:71], v208 offset:0
	ds_read_b128 v[72:75], v208 offset:0x2000
	v_add_u32_e32 v209, s52, v175
	ds_read_b128 v[204:207], v209 offset:0
	ds_read_b128 v[216:219], v209 offset:0x2000
	v_add_u32_e32 v210, s52, v176
	ds_read_b128 v[220:223], v210 offset:0
	ds_read_b128 v[224:227], v210 offset:0x2000
	v_add_u32_e32 v211, s52, v177
	ds_read_b128 v[228:231], v211 offset:0
	ds_read_b128 v[232:235], v211 offset:0x2000
	s_waitcnt lgkmcnt(4)
	v_mfma_f32_32x32x16_bf16 v[84:99], v[68:71], v[128:131], 0
	v_mfma_f32_32x32x16_bf16 v[68:83], v[72:75], v[128:131], 0
	v_mfma_f32_32x32x16_bf16 v[84:99], v[204:207], v[124:127], v[84:99]
	v_mfma_f32_32x32x16_bf16 v[68:83], v[216:219], v[124:127], v[68:83]
	ds_read_b128 v[204:207], v208 offset:0x80
	ds_read_b128 v[216:219], v208 offset:0x2080
	ds_read_b128 v[236:239], v209 offset:0x80
	ds_read_b128 v[242:245], v209 offset:0x2080
	s_waitcnt lgkmcnt(4)
	v_mfma_f32_32x32x16_bf16 v[84:99], v[220:223], v[120:123], v[84:99]
	v_mfma_f32_32x32x16_bf16 v[68:83], v[224:227], v[120:123], v[68:83]
	v_mfma_f32_32x32x16_bf16 v[84:99], v[228:231], v[116:119], v[84:99]
	v_mfma_f32_32x32x16_bf16 v[68:83], v[232:235], v[116:119], v[68:83]
	ds_read_b128 v[220:223], v210 offset:0x80
	ds_read_b128 v[224:227], v210 offset:0x2080
	ds_read_b128 v[228:231], v211 offset:0x80
	ds_read_b128 v[232:235], v211 offset:0x2080
	s_waitcnt lgkmcnt(4)
	v_mfma_f32_32x32x16_bf16 v[84:99], v[204:207], v[112:115], v[84:99]
	v_mfma_f32_32x32x16_bf16 v[68:83], v[216:219], v[112:115], v[68:83]
	v_mfma_f32_32x32x16_bf16 v[84:99], v[236:239], v[108:111], v[84:99]
	v_mfma_f32_32x32x16_bf16 v[68:83], v[242:245], v[108:111], v[68:83]
	s_waitcnt lgkmcnt(0)
	v_mfma_f32_32x32x16_bf16 v[84:99], v[220:223], v[104:107], v[84:99]
	v_mfma_f32_32x32x16_bf16 v[68:83], v[224:227], v[104:107], v[68:83]
	v_mfma_f32_32x32x16_bf16 v[84:99], v[228:231], v[100:103], v[84:99]
	v_mfma_f32_32x32x16_bf16 v[68:83], v[232:235], v[100:103], v[68:83]
	ds_read_b64_tr_b16 v[204:205], v187 offset:0x200
	ds_read_b64_tr_b16 v[206:207], v187 offset:0xa00
	ds_read_b64_tr_b16 v[216:217], v187 offset:0x1200
	ds_read_b64_tr_b16 v[218:219], v187 offset:0x1a00
	ds_read_b64_tr_b16 v[220:221], v187 offset:0x2200
	ds_read_b64_tr_b16 v[222:223], v187 offset:0x2a00
	ds_read_b64_tr_b16 v[224:225], v187 offset:0x3200
	ds_read_b64_tr_b16 v[226:227], v187 offset:0x3a00
	s_waitcnt lgkmcnt(8)
	v_mfma_f32_32x32x16_bf16 v[4:19], v[148:151], v[188:191], v[4:19]
	s_lshl_b32 s19, s51, 14
	s_add_i32 s8, s19, 0
	v_add_u32_e32 v236, s8, v179
	s_waitcnt vmcnt(0)
	v_mfma_f32_32x32x16_bf16 v[4:19], v[152:155], v[192:195], v[4:19]
	ds_write_b128 v236, v[144:147]
	v_add_u32_e32 v236, s8, v178
	v_mfma_f32_32x32x16_bf16 v[4:19], v[156:159], v[196:199], v[4:19]
	ds_write_b128 v236, v[136:139]
	v_add_u32_e32 v236, s8, v180
	v_mfma_f32_32x32x16_bf16 v[4:19], v[160:163], v[200:203], v[4:19]
	ds_read_b64_tr_b16 v[188:189], v187 offset:0x400
	ds_read_b64_tr_b16 v[190:191], v187 offset:0xc00
	ds_read_b64_tr_b16 v[192:193], v187 offset:0x1400
	ds_read_b64_tr_b16 v[194:195], v187 offset:0x1c00
	ds_read_b64_tr_b16 v[196:197], v187 offset:0x2400
	ds_read_b64_tr_b16 v[198:199], v187 offset:0x2c00
	ds_read_b64_tr_b16 v[200:201], v187 offset:0x3400
	ds_read_b64_tr_b16 v[202:203], v187 offset:0x3c00
	s_waitcnt lgkmcnt(10)
	v_mfma_f32_32x32x16_bf16 v[52:67], v[148:151], v[204:207], v[52:67]
	ds_write_b128 v236, v[140:143] offset:49152
	v_add_u32_e32 v236, s8, v181
	v_mfma_f32_32x32x16_bf16 v[52:67], v[152:155], v[216:219], v[52:67]
	ds_write_b128 v236, v[132:135] offset:49152
	s_add_i32 s48, s48, 1
	v_mfma_f32_32x32x16_bf16 v[52:67], v[156:159], v[220:223], v[52:67]
	s_sub_i32 s8, s50, s47
	s_min_u32 s36, s50, s8
	s_lshl_b64 s[8:9], s[36:37], 10
	s_cmp_lt_u32 s50, s47
	s_cselect_b32 s16, s30, s20
	s_cselect_b32 s17, s31, s21
	v_mfma_f32_32x32x16_bf16 v[52:67], v[160:163], v[224:227], v[52:67]
	ds_read_b64_tr_b16 v[204:205], v187 offset:0x600
	ds_read_b64_tr_b16 v[206:207], v187 offset:0xe00
	ds_read_b64_tr_b16 v[216:217], v187 offset:0x1600
	ds_read_b64_tr_b16 v[218:219], v187 offset:0x1e00
	ds_read_b64_tr_b16 v[220:221], v187 offset:0x2600
	ds_read_b64_tr_b16 v[222:223], v187 offset:0x2e00
	ds_read_b64_tr_b16 v[224:225], v187 offset:0x3600
	ds_read_b64_tr_b16 v[226:227], v187 offset:0x3e00
	s_waitcnt lgkmcnt(10)
	v_mfma_f32_32x32x16_bf16 v[36:51], v[148:151], v[188:191], v[36:51]
	s_cselect_b32 s36, s42, s26
	s_cselect_b32 s54, s43, s27
	s_add_u32 s16, s16, s8
	s_addc_u32 s17, s17, s9
	s_add_u32 s8, s36, s8
	s_addc_u32 s9, s54, s9
	v_mfma_f32_32x32x16_bf16 v[36:51], v[152:155], v[192:195], v[36:51]
	global_load_dwordx4 v[144:147], v2, s[8:9]
	s_add_u32 s8, s8, 0x8000
	s_addc_u32 s9, s9, 0
	v_mfma_f32_32x32x16_bf16 v[36:51], v[156:159], v[196:199], v[36:51]
	global_load_dwordx4 v[136:139], v2, s[8:9]
	global_load_dwordx4 v[140:143], v2, s[16:17]
	v_mfma_f32_32x32x16_bf16 v[36:51], v[160:163], v[200:203], v[36:51]
	s_add_u32 s16, s16, 0x8000
	s_addc_u32 s17, s17, 0
	global_load_dwordx4 v[132:135], v2, s[16:17]
	s_waitcnt lgkmcnt(0)
	v_mfma_f32_32x32x16_bf16 v[20:35], v[148:151], v[204:207], v[20:35]
	v_mfma_f32_32x32x16_bf16 v[20:35], v[152:155], v[216:219], v[20:35]
	v_mfma_f32_32x32x16_bf16 v[20:35], v[156:159], v[220:223], v[20:35]
	v_mfma_f32_32x32x16_bf16 v[20:35], v[160:163], v[224:227], v[20:35]
